# SwiGLU epilogue: packed f32 multiplies/adds (g*u*rs^2 and g*rs*(-log2e)), 18 fewer VALU per 8 outputs
# speedup vs baseline: 1.0093x; 1.0073x over previous
; __device__ __forceinline__ unsigned cvt_pk_bf16(float lo, float hi) { unsigned r; asm volatile("v_cvt_pk_bf16_f32 %0, %1, %2" : "=v"(r) : "v"(lo), "v"(hi)); return r; }
;     __device__ __forceinline__ void operator()(const f32x4 (&acc)[2][2][4][2], const Unit& u, int wr, int wc, int fr, int fq) const {
;     ...
;             for (int m = 0; m < 4; ++m) { const int row = row0 + ai * HALF + m * 16; const f32x4 q0 = *(const f32x4*)(ssq + (size_t)row * 16), q1 = *(const f32x4*)(ssq + (size_t)row * 16 + 4), q2 = *(const f32x4*)(ssq + (size_t)row * 16 + 8), q3 = *(const f32x4*)(ssq + (size_t)row * 16 + 12);
;                 const float rs = rsqrtf(((((q0[0] + q0[1]) + (q0[2] + q0[3])) + ((q1[0] + q1[1]) + (q1[2] + q1[3]))) + (((q2[0] + q2[1]) + (q2[2] + q2[3])) + ((q3[0] + q3[1]) + (q3[2] + q3[3])))) * (1.0f / 1024.0f) + 1e-6f);
;                 float a[8];
; #pragma unroll
;                 for (int n = 0; n < 2; ++n)
; #pragma unroll
;                     for (int j = 0; j < 4; ++j) { const float g = acc[ai][0][m][n][j] * rs, up = acc[ai][1][m][n][j] * rs; a[4 * n + j] = g * up * __builtin_amdgcn_rcpf(1.0f + __expf(-g)); }
;                 u32x4 w; w.x = cvt_pk_bf16(a[0], a[1]); w.y = cvt_pk_bf16(a[2], a[3]); w.z = cvt_pk_bf16(a[4], a[5]); w.w = cvt_pk_bf16(a[6], a[7]);
;                 *(u32x4*)(O + (size_t)row * ldc + col0) = w; }
.LBB0_610:
	v_readlane_b32 s28, v253, 45
	v_readlane_b32 s29, v253, 46
	v_lshl_add_u32 v192, s55, 8, v147
	v_and_b32_e32 v193, 24, v149
	v_lshlrev_b32_e32 v193, 1, v193
	v_lshl_add_u32 v193, v192, 6, v193
	v_add_u32_e32 v230, 0x2000, v193
	global_load_dwordx4 v[152:155], v193, s[16:17]
	global_load_dwordx4 v[156:159], v193, s[16:17] offset:1024
	global_load_dwordx4 v[160:163], v193, s[16:17] offset:2048
	global_load_dwordx4 v[164:167], v193, s[16:17] offset:3072
	global_load_dwordx4 v[168:171], v230, s[16:17]
	global_load_dwordx4 v[172:175], v230, s[16:17] offset:1024
	global_load_dwordx4 v[176:179], v230, s[16:17] offset:2048
	global_load_dwordx4 v[180:183], v230, s[16:17] offset:3072
	v_xor_b32_e32 v228, 16, v214
	v_lshlrev_b32_e32 v228, 2, v228
	v_xor_b32_e32 v229, 32, v214
	v_lshlrev_b32_e32 v229, 2, v229
	s_movk_i32 s21, 0x1600
	v_lshl_or_b32 v231, s54, 7, v149
	v_lshlrev_b32_e32 v231, 1, v231
	v_mad_u32_u24 v184, v192, s21, v231
	v_add_u32_e32 v185, 0x16000, v184
	v_add_u32_e32 v186, 0x16000, v185
	v_add_u32_e32 v187, 0x16000, v186
	v_add_u32_e32 v188, 0xb0000, v184
	v_add_u32_e32 v189, 0xb0000, v185
	v_add_u32_e32 v190, 0xb0000, v186
	v_add_u32_e32 v191, 0xb0000, v187
	s_waitcnt vmcnt(7)
	v_add_f32_e32 v154, v154, v155
	v_add_f32_e32 v194, v152, v153
	v_add_f32_e32 v194, v194, v154
	s_waitcnt vmcnt(6)
	v_add_f32_e32 v158, v158, v159
	v_add_f32_e32 v195, v156, v157
	v_add_f32_e32 v195, v195, v158
	s_waitcnt vmcnt(5)
	v_add_f32_e32 v162, v162, v163
	v_add_f32_e32 v196, v160, v161
	v_add_f32_e32 v196, v196, v162
	s_waitcnt vmcnt(4)
	v_add_f32_e32 v166, v166, v167
	v_add_f32_e32 v197, v164, v165
	v_add_f32_e32 v197, v197, v166
	s_waitcnt vmcnt(3)
	v_add_f32_e32 v170, v170, v171
	v_add_f32_e32 v204, v168, v169
	v_add_f32_e32 v204, v204, v170
	s_waitcnt vmcnt(2)
	v_add_f32_e32 v174, v174, v175
	v_add_f32_e32 v205, v172, v173
	v_add_f32_e32 v205, v205, v174
	s_waitcnt vmcnt(1)
	v_add_f32_e32 v178, v178, v179
	v_add_f32_e32 v206, v176, v177
	v_add_f32_e32 v206, v206, v178
	s_waitcnt vmcnt(0)
	v_add_f32_e32 v182, v182, v183
	v_add_f32_e32 v207, v180, v181
	v_add_f32_e32 v207, v207, v182
	ds_bpermute_b32 v220, v228, v194
	ds_bpermute_b32 v221, v228, v195
	ds_bpermute_b32 v222, v228, v196
	ds_bpermute_b32 v223, v228, v197
	ds_bpermute_b32 v224, v228, v204
	ds_bpermute_b32 v225, v228, v205
	ds_bpermute_b32 v226, v228, v206
	ds_bpermute_b32 v227, v228, v207
	s_waitcnt lgkmcnt(7)
	v_add_f32_e32 v194, v194, v220
	s_waitcnt lgkmcnt(6)
	v_add_f32_e32 v195, v195, v221
	s_waitcnt lgkmcnt(5)
	v_add_f32_e32 v196, v196, v222
	s_waitcnt lgkmcnt(4)
	v_add_f32_e32 v197, v197, v223
	s_waitcnt lgkmcnt(3)
	v_add_f32_e32 v204, v204, v224
	s_waitcnt lgkmcnt(2)
	v_add_f32_e32 v205, v205, v225
	s_waitcnt lgkmcnt(1)
	v_add_f32_e32 v206, v206, v226
	s_waitcnt lgkmcnt(0)
	v_add_f32_e32 v207, v207, v227
	ds_bpermute_b32 v220, v229, v194
	ds_bpermute_b32 v221, v229, v195
	ds_bpermute_b32 v222, v229, v196
	ds_bpermute_b32 v223, v229, v197
	ds_bpermute_b32 v224, v229, v204
	ds_bpermute_b32 v225, v229, v205
	ds_bpermute_b32 v226, v229, v206
	ds_bpermute_b32 v227, v229, v207
	s_waitcnt lgkmcnt(7)
	v_add_f32_e32 v194, v194, v220
	s_waitcnt lgkmcnt(6)
	v_add_f32_e32 v195, v195, v221
	s_waitcnt lgkmcnt(5)
	v_add_f32_e32 v196, v196, v222
	s_waitcnt lgkmcnt(4)
	v_add_f32_e32 v197, v197, v223
	s_waitcnt lgkmcnt(3)
	v_add_f32_e32 v204, v204, v224
	s_waitcnt lgkmcnt(2)
	v_add_f32_e32 v205, v205, v225
	s_waitcnt lgkmcnt(1)
	v_add_f32_e32 v206, v206, v226
	s_waitcnt lgkmcnt(0)
	v_add_f32_e32 v207, v207, v227
	v_fmamk_f32 v194, v194, 0x3a800000, v208
	v_fmamk_f32 v195, v195, 0x3a800000, v208
	v_fmamk_f32 v196, v196, 0x3a800000, v208
	v_fmamk_f32 v197, v197, 0x3a800000, v208
	v_fmamk_f32 v204, v204, 0x3a800000, v208
	v_fmamk_f32 v205, v205, 0x3a800000, v208
	v_fmamk_f32 v206, v206, 0x3a800000, v208
	v_fmamk_f32 v207, v207, 0x3a800000, v208
	v_rsq_f32_e32 v152, v194
	v_rsq_f32_e32 v156, v195
	v_rsq_f32_e32 v160, v196
	v_rsq_f32_e32 v164, v197
	v_rsq_f32_e32 v168, v204
	v_rsq_f32_e32 v172, v205
	v_rsq_f32_e32 v176, v206
	v_rsq_f32_e32 v180, v207
	v_mov_b32_e32 v220, 1.0
	v_mul_f32_e32 v154, 0xbfb8aa3b, v152
	v_mul_f32_e32 v152, v152, v152
	v_pk_mul_f32 v[124:125], v[128:129], v[124:125]
	v_pk_mul_f32 v[126:127], v[130:131], v[126:127]
	v_pk_mul_f32 v[116:117], v[120:121], v[116:117]
	v_pk_mul_f32 v[118:119], v[122:123], v[118:119]
	v_pk_mul_f32 v[128:129], v[128:129], v[154:155] op_sel_hi:[1,0]
	v_pk_mul_f32 v[130:131], v[130:131], v[154:155] op_sel_hi:[1,0]
	v_pk_mul_f32 v[120:121], v[120:121], v[154:155] op_sel_hi:[1,0]
	v_pk_mul_f32 v[122:123], v[122:123], v[154:155] op_sel_hi:[1,0]
	v_pk_mul_f32 v[124:125], v[124:125], v[152:153] op_sel_hi:[1,0]
	v_pk_mul_f32 v[126:127], v[126:127], v[152:153] op_sel_hi:[1,0]
	v_pk_mul_f32 v[116:117], v[116:117], v[152:153] op_sel_hi:[1,0]
	v_pk_mul_f32 v[118:119], v[118:119], v[152:153] op_sel_hi:[1,0]
	v_exp_f32_e32 v128, v128
	v_exp_f32_e32 v129, v129
	v_exp_f32_e32 v130, v130
	v_exp_f32_e32 v131, v131
	v_exp_f32_e32 v120, v120
	v_exp_f32_e32 v121, v121
	v_exp_f32_e32 v122, v122
	v_exp_f32_e32 v123, v123
	v_pk_add_f32 v[128:129], v[128:129], v[220:221] op_sel_hi:[1,0]
	v_pk_add_f32 v[130:131], v[130:131], v[220:221] op_sel_hi:[1,0]
	v_pk_add_f32 v[120:121], v[120:121], v[220:221] op_sel_hi:[1,0]
	v_pk_add_f32 v[122:123], v[122:123], v[220:221] op_sel_hi:[1,0]
	v_rcp_f32_e32 v128, v128
	v_rcp_f32_e32 v129, v129
	v_rcp_f32_e32 v130, v130
	v_rcp_f32_e32 v131, v131
	v_rcp_f32_e32 v120, v120
	v_rcp_f32_e32 v121, v121
	v_rcp_f32_e32 v122, v122
	v_rcp_f32_e32 v123, v123
	v_pk_mul_f32 v[128:129], v[124:125], v[128:129]
	v_pk_mul_f32 v[130:131], v[126:127], v[130:131]
; __device__ __forceinline__ unsigned cvt_pk_bf16(float lo, float hi) { unsigned r; asm volatile("v_cvt_pk_bf16_f32 %0, %1, %2" : "=v"(r) : "v"(lo), "v"(hi)); return r; }
;     __device__ __forceinline__ void operator()(const f32x4 (&acc)[2][2][4][2], const Unit& u, int wr, int wc, int fr, int fq) const {
;     ...
;             for (int m = 0; m < 4; ++m) { const int row = row0 + ai * HALF + m * 16; const f32x4 q0 = *(const f32x4*)(ssq + (size_t)row * 16), q1 = *(const f32x4*)(ssq + (size_t)row * 16 + 4), q2 = *(const f32x4*)(ssq + (size_t)row * 16 + 8), q3 = *(const f32x4*)(ssq + (size_t)row * 16 + 12);
;                 const float rs = rsqrtf(((((q0[0] + q0[1]) + (q0[2] + q0[3])) + ((q1[0] + q1[1]) + (q1[2] + q1[3]))) + (((q2[0] + q2[1]) + (q2[2] + q2[3])) + ((q3[0] + q3[1]) + (q3[2] + q3[3])))) * (1.0f / 1024.0f) + 1e-6f);
;                 float a[8];
; #pragma unroll
;                 for (int n = 0; n < 2; ++n)
; #pragma unroll
;                     for (int j = 0; j < 4; ++j) { const float g = acc[ai][0][m][n][j] * rs, up = acc[ai][1][m][n][j] * rs; a[4 * n + j] = g * up * __builtin_amdgcn_rcpf(1.0f + __expf(-g)); }
;                 u32x4 w; w.x = cvt_pk_bf16(a[0], a[1]); w.y = cvt_pk_bf16(a[2], a[3]); w.z = cvt_pk_bf16(a[4], a[5]); w.w = cvt_pk_bf16(a[6], a[7]);
;                 *(u32x4*)(O + (size_t)row * ldc + col0) = w; }
	v_pk_mul_f32 v[120:121], v[116:117], v[120:121]
	v_pk_mul_f32 v[122:123], v[118:119], v[122:123]
	v_cvt_pk_bf16_f32 v128, v128, v129
	v_cvt_pk_bf16_f32 v129, v130, v131
	v_cvt_pk_bf16_f32 v130, v120, v121
	v_cvt_pk_bf16_f32 v131, v122, v123
	global_store_dwordx4 v184, v[128:131], s[28:29]
	v_mul_f32_e32 v158, 0xbfb8aa3b, v156
	v_mul_f32_e32 v156, v156, v156
	v_pk_mul_f32 v[108:109], v[112:113], v[108:109]
	v_pk_mul_f32 v[110:111], v[114:115], v[110:111]
	v_pk_mul_f32 v[100:101], v[104:105], v[100:101]
	v_pk_mul_f32 v[102:103], v[106:107], v[102:103]
	v_pk_mul_f32 v[112:113], v[112:113], v[158:159] op_sel_hi:[1,0]
	v_pk_mul_f32 v[114:115], v[114:115], v[158:159] op_sel_hi:[1,0]
	v_pk_mul_f32 v[104:105], v[104:105], v[158:159] op_sel_hi:[1,0]
	v_pk_mul_f32 v[106:107], v[106:107], v[158:159] op_sel_hi:[1,0]
	v_pk_mul_f32 v[108:109], v[108:109], v[156:157] op_sel_hi:[1,0]
	v_pk_mul_f32 v[110:111], v[110:111], v[156:157] op_sel_hi:[1,0]
	v_pk_mul_f32 v[100:101], v[100:101], v[156:157] op_sel_hi:[1,0]
	v_pk_mul_f32 v[102:103], v[102:103], v[156:157] op_sel_hi:[1,0]
	v_exp_f32_e32 v112, v112
	v_exp_f32_e32 v113, v113
	v_exp_f32_e32 v114, v114
	v_exp_f32_e32 v115, v115
	v_exp_f32_e32 v104, v104
	v_exp_f32_e32 v105, v105
	v_exp_f32_e32 v106, v106
	v_exp_f32_e32 v107, v107
	v_pk_add_f32 v[112:113], v[112:113], v[220:221] op_sel_hi:[1,0]
	v_pk_add_f32 v[114:115], v[114:115], v[220:221] op_sel_hi:[1,0]
	v_pk_add_f32 v[104:105], v[104:105], v[220:221] op_sel_hi:[1,0]
	v_pk_add_f32 v[106:107], v[106:107], v[220:221] op_sel_hi:[1,0]
	v_rcp_f32_e32 v112, v112
	v_rcp_f32_e32 v113, v113
	v_rcp_f32_e32 v114, v114
	v_rcp_f32_e32 v115, v115
	v_rcp_f32_e32 v104, v104
	v_rcp_f32_e32 v105, v105
	v_rcp_f32_e32 v106, v106
	v_rcp_f32_e32 v107, v107
	v_pk_mul_f32 v[112:113], v[108:109], v[112:113]
	v_pk_mul_f32 v[114:115], v[110:111], v[114:115]
	v_pk_mul_f32 v[104:105], v[100:101], v[104:105]
	v_pk_mul_f32 v[106:107], v[102:103], v[106:107]
	v_cvt_pk_bf16_f32 v112, v112, v113
	v_cvt_pk_bf16_f32 v113, v114, v115
	v_cvt_pk_bf16_f32 v114, v104, v105
	v_cvt_pk_bf16_f32 v115, v106, v107
	global_store_dwordx4 v185, v[112:115], s[28:29]
	v_mul_f32_e32 v162, 0xbfb8aa3b, v160
	v_mul_f32_e32 v160, v160, v160
	v_pk_mul_f32 v[92:93], v[96:97], v[92:93]
	v_pk_mul_f32 v[94:95], v[98:99], v[94:95]
	v_pk_mul_f32 v[84:85], v[88:89], v[84:85]
	v_pk_mul_f32 v[86:87], v[90:91], v[86:87]
	v_pk_mul_f32 v[96:97], v[96:97], v[162:163] op_sel_hi:[1,0]
	v_pk_mul_f32 v[98:99], v[98:99], v[162:163] op_sel_hi:[1,0]
	v_pk_mul_f32 v[88:89], v[88:89], v[162:163] op_sel_hi:[1,0]
	v_pk_mul_f32 v[90:91], v[90:91], v[162:163] op_sel_hi:[1,0]
	v_pk_mul_f32 v[92:93], v[92:93], v[160:161] op_sel_hi:[1,0]
	v_pk_mul_f32 v[94:95], v[94:95], v[160:161] op_sel_hi:[1,0]
	v_pk_mul_f32 v[84:85], v[84:85], v[160:161] op_sel_hi:[1,0]
	v_pk_mul_f32 v[86:87], v[86:87], v[160:161] op_sel_hi:[1,0]
	v_exp_f32_e32 v96, v96
	v_exp_f32_e32 v97, v97
	v_exp_f32_e32 v98, v98
	v_exp_f32_e32 v99, v99
	v_exp_f32_e32 v88, v88
	v_exp_f32_e32 v89, v89
	v_exp_f32_e32 v90, v90
	v_exp_f32_e32 v91, v91
	v_pk_add_f32 v[96:97], v[96:97], v[220:221] op_sel_hi:[1,0]
	v_pk_add_f32 v[98:99], v[98:99], v[220:221] op_sel_hi:[1,0]
	v_pk_add_f32 v[88:89], v[88:89], v[220:221] op_sel_hi:[1,0]
	v_pk_add_f32 v[90:91], v[90:91], v[220:221] op_sel_hi:[1,0]
	v_rcp_f32_e32 v96, v96
	v_rcp_f32_e32 v97, v97
	v_rcp_f32_e32 v98, v98
	v_rcp_f32_e32 v99, v99
	v_rcp_f32_e32 v88, v88
	v_rcp_f32_e32 v89, v89
	v_rcp_f32_e32 v90, v90
	v_rcp_f32_e32 v91, v91
	v_pk_mul_f32 v[96:97], v[92:93], v[96:97]
	v_pk_mul_f32 v[98:99], v[94:95], v[98:99]
	v_pk_mul_f32 v[88:89], v[84:85], v[88:89]
	v_pk_mul_f32 v[90:91], v[86:87], v[90:91]
	v_cvt_pk_bf16_f32 v96, v96, v97
	v_cvt_pk_bf16_f32 v97, v98, v99
	v_cvt_pk_bf16_f32 v98, v88, v89
	v_cvt_pk_bf16_f32 v99, v90, v91
	global_store_dwordx4 v186, v[96:99], s[28:29]
	v_mul_f32_e32 v166, 0xbfb8aa3b, v164
	v_mul_f32_e32 v164, v164, v164
	v_pk_mul_f32 v[76:77], v[80:81], v[76:77]
	v_pk_mul_f32 v[78:79], v[82:83], v[78:79]
	v_pk_mul_f32 v[68:69], v[72:73], v[68:69]
	v_pk_mul_f32 v[70:71], v[74:75], v[70:71]
	v_pk_mul_f32 v[80:81], v[80:81], v[166:167] op_sel_hi:[1,0]
	v_pk_mul_f32 v[82:83], v[82:83], v[166:167] op_sel_hi:[1,0]
	v_pk_mul_f32 v[72:73], v[72:73], v[166:167] op_sel_hi:[1,0]
	v_pk_mul_f32 v[74:75], v[74:75], v[166:167] op_sel_hi:[1,0]
	v_pk_mul_f32 v[76:77], v[76:77], v[164:165] op_sel_hi:[1,0]
	v_pk_mul_f32 v[78:79], v[78:79], v[164:165] op_sel_hi:[1,0]
	v_pk_mul_f32 v[68:69], v[68:69], v[164:165] op_sel_hi:[1,0]
	v_pk_mul_f32 v[70:71], v[70:71], v[164:165] op_sel_hi:[1,0]
	v_exp_f32_e32 v80, v80
	v_exp_f32_e32 v81, v81
	v_exp_f32_e32 v82, v82
	v_exp_f32_e32 v83, v83
	v_exp_f32_e32 v72, v72
	v_exp_f32_e32 v73, v73
	v_exp_f32_e32 v74, v74
	v_exp_f32_e32 v75, v75
	v_pk_add_f32 v[80:81], v[80:81], v[220:221] op_sel_hi:[1,0]
	v_pk_add_f32 v[82:83], v[82:83], v[220:221] op_sel_hi:[1,0]
	v_pk_add_f32 v[72:73], v[72:73], v[220:221] op_sel_hi:[1,0]
	v_pk_add_f32 v[74:75], v[74:75], v[220:221] op_sel_hi:[1,0]
	v_rcp_f32_e32 v80, v80
	v_rcp_f32_e32 v81, v81
	v_rcp_f32_e32 v82, v82
	v_rcp_f32_e32 v83, v83
	v_rcp_f32_e32 v72, v72
	v_rcp_f32_e32 v73, v73
	v_rcp_f32_e32 v74, v74
	v_rcp_f32_e32 v75, v75
	v_pk_mul_f32 v[80:81], v[76:77], v[80:81]
	v_pk_mul_f32 v[82:83], v[78:79], v[82:83]
	v_pk_mul_f32 v[72:73], v[68:69], v[72:73]
	v_pk_mul_f32 v[74:75], v[70:71], v[74:75]
	v_cvt_pk_bf16_f32 v80, v80, v81
	v_cvt_pk_bf16_f32 v81, v82, v83
	v_cvt_pk_bf16_f32 v82, v72, v73
	v_cvt_pk_bf16_f32 v83, v74, v75
	global_store_dwordx4 v187, v[80:83], s[28:29]
	v_mul_f32_e32 v170, 0xbfb8aa3b, v168
	v_mul_f32_e32 v168, v168, v168
; __device__ __forceinline__ unsigned cvt_pk_bf16(float lo, float hi) { unsigned r; asm volatile("v_cvt_pk_bf16_f32 %0, %1, %2" : "=v"(r) : "v"(lo), "v"(hi)); return r; }
;     __device__ __forceinline__ void operator()(const f32x4 (&acc)[2][2][4][2], const Unit& u, int wr, int wc, int fr, int fq) const {
;     ...
;             for (int m = 0; m < 4; ++m) { const int row = row0 + ai * HALF + m * 16; const f32x4 q0 = *(const f32x4*)(ssq + (size_t)row * 16), q1 = *(const f32x4*)(ssq + (size_t)row * 16 + 4), q2 = *(const f32x4*)(ssq + (size_t)row * 16 + 8), q3 = *(const f32x4*)(ssq + (size_t)row * 16 + 12);
;                 const float rs = rsqrtf(((((q0[0] + q0[1]) + (q0[2] + q0[3])) + ((q1[0] + q1[1]) + (q1[2] + q1[3]))) + (((q2[0] + q2[1]) + (q2[2] + q2[3])) + ((q3[0] + q3[1]) + (q3[2] + q3[3])))) * (1.0f / 1024.0f) + 1e-6f);
;                 float a[8];
; #pragma unroll
;                 for (int n = 0; n < 2; ++n)
; #pragma unroll
;                     for (int j = 0; j < 4; ++j) { const float g = acc[ai][0][m][n][j] * rs, up = acc[ai][1][m][n][j] * rs; a[4 * n + j] = g * up * __builtin_amdgcn_rcpf(1.0f + __expf(-g)); }
;                 u32x4 w; w.x = cvt_pk_bf16(a[0], a[1]); w.y = cvt_pk_bf16(a[2], a[3]); w.z = cvt_pk_bf16(a[4], a[5]); w.w = cvt_pk_bf16(a[6], a[7]);
;                 *(u32x4*)(O + (size_t)row * ldc + col0) = w; }
	v_pk_mul_f32 v[60:61], v[64:65], v[60:61]
	v_pk_mul_f32 v[62:63], v[66:67], v[62:63]
	v_pk_mul_f32 v[52:53], v[56:57], v[52:53]
	v_pk_mul_f32 v[54:55], v[58:59], v[54:55]
	v_pk_mul_f32 v[64:65], v[64:65], v[170:171] op_sel_hi:[1,0]
	v_pk_mul_f32 v[66:67], v[66:67], v[170:171] op_sel_hi:[1,0]
	v_pk_mul_f32 v[56:57], v[56:57], v[170:171] op_sel_hi:[1,0]
	v_pk_mul_f32 v[58:59], v[58:59], v[170:171] op_sel_hi:[1,0]
	v_pk_mul_f32 v[60:61], v[60:61], v[168:169] op_sel_hi:[1,0]
	v_pk_mul_f32 v[62:63], v[62:63], v[168:169] op_sel_hi:[1,0]
	v_pk_mul_f32 v[52:53], v[52:53], v[168:169] op_sel_hi:[1,0]
	v_pk_mul_f32 v[54:55], v[54:55], v[168:169] op_sel_hi:[1,0]
	v_exp_f32_e32 v64, v64
	v_exp_f32_e32 v65, v65
	v_exp_f32_e32 v66, v66
	v_exp_f32_e32 v67, v67
	v_exp_f32_e32 v56, v56
	v_exp_f32_e32 v57, v57
	v_exp_f32_e32 v58, v58
	v_exp_f32_e32 v59, v59
	v_pk_add_f32 v[64:65], v[64:65], v[220:221] op_sel_hi:[1,0]
	v_pk_add_f32 v[66:67], v[66:67], v[220:221] op_sel_hi:[1,0]
	v_pk_add_f32 v[56:57], v[56:57], v[220:221] op_sel_hi:[1,0]
	v_pk_add_f32 v[58:59], v[58:59], v[220:221] op_sel_hi:[1,0]
	v_rcp_f32_e32 v64, v64
	v_rcp_f32_e32 v65, v65
	v_rcp_f32_e32 v66, v66
	v_rcp_f32_e32 v67, v67
	v_rcp_f32_e32 v56, v56
	v_rcp_f32_e32 v57, v57
	v_rcp_f32_e32 v58, v58
	v_rcp_f32_e32 v59, v59
	v_pk_mul_f32 v[64:65], v[60:61], v[64:65]
	v_pk_mul_f32 v[66:67], v[62:63], v[66:67]
	v_pk_mul_f32 v[56:57], v[52:53], v[56:57]
	v_pk_mul_f32 v[58:59], v[54:55], v[58:59]
	v_cvt_pk_bf16_f32 v64, v64, v65
	v_cvt_pk_bf16_f32 v65, v66, v67
	v_cvt_pk_bf16_f32 v66, v56, v57
	v_cvt_pk_bf16_f32 v67, v58, v59
	global_store_dwordx4 v188, v[64:67], s[28:29]
	v_mul_f32_e32 v174, 0xbfb8aa3b, v172
	v_mul_f32_e32 v172, v172, v172
	v_pk_mul_f32 v[44:45], v[48:49], v[44:45]
	v_pk_mul_f32 v[46:47], v[50:51], v[46:47]
	v_pk_mul_f32 v[36:37], v[40:41], v[36:37]
	v_pk_mul_f32 v[38:39], v[42:43], v[38:39]
	v_pk_mul_f32 v[48:49], v[48:49], v[174:175] op_sel_hi:[1,0]
	v_pk_mul_f32 v[50:51], v[50:51], v[174:175] op_sel_hi:[1,0]
	v_pk_mul_f32 v[40:41], v[40:41], v[174:175] op_sel_hi:[1,0]
	v_pk_mul_f32 v[42:43], v[42:43], v[174:175] op_sel_hi:[1,0]
	v_pk_mul_f32 v[44:45], v[44:45], v[172:173] op_sel_hi:[1,0]
	v_pk_mul_f32 v[46:47], v[46:47], v[172:173] op_sel_hi:[1,0]
	v_pk_mul_f32 v[36:37], v[36:37], v[172:173] op_sel_hi:[1,0]
	v_pk_mul_f32 v[38:39], v[38:39], v[172:173] op_sel_hi:[1,0]
	v_exp_f32_e32 v48, v48
	v_exp_f32_e32 v49, v49
	v_exp_f32_e32 v50, v50
	v_exp_f32_e32 v51, v51
	v_exp_f32_e32 v40, v40
	v_exp_f32_e32 v41, v41
	v_exp_f32_e32 v42, v42
	v_exp_f32_e32 v43, v43
	v_pk_add_f32 v[48:49], v[48:49], v[220:221] op_sel_hi:[1,0]
	v_pk_add_f32 v[50:51], v[50:51], v[220:221] op_sel_hi:[1,0]
	v_pk_add_f32 v[40:41], v[40:41], v[220:221] op_sel_hi:[1,0]
	v_pk_add_f32 v[42:43], v[42:43], v[220:221] op_sel_hi:[1,0]
	v_rcp_f32_e32 v48, v48
	v_rcp_f32_e32 v49, v49
	v_rcp_f32_e32 v50, v50
	v_rcp_f32_e32 v51, v51
	v_rcp_f32_e32 v40, v40
	v_rcp_f32_e32 v41, v41
	v_rcp_f32_e32 v42, v42
	v_rcp_f32_e32 v43, v43
	v_pk_mul_f32 v[48:49], v[44:45], v[48:49]
	v_pk_mul_f32 v[50:51], v[46:47], v[50:51]
	v_pk_mul_f32 v[40:41], v[36:37], v[40:41]
	v_pk_mul_f32 v[42:43], v[38:39], v[42:43]
	v_cvt_pk_bf16_f32 v48, v48, v49
	v_cvt_pk_bf16_f32 v49, v50, v51
	v_cvt_pk_bf16_f32 v50, v40, v41
	v_cvt_pk_bf16_f32 v51, v42, v43
	global_store_dwordx4 v189, v[48:51], s[28:29]
	v_mul_f32_e32 v178, 0xbfb8aa3b, v176
	v_mul_f32_e32 v176, v176, v176
	v_pk_mul_f32 v[28:29], v[32:33], v[28:29]
	v_pk_mul_f32 v[30:31], v[34:35], v[30:31]
	v_pk_mul_f32 v[20:21], v[24:25], v[20:21]
	v_pk_mul_f32 v[22:23], v[26:27], v[22:23]
	v_pk_mul_f32 v[32:33], v[32:33], v[178:179] op_sel_hi:[1,0]
	v_pk_mul_f32 v[34:35], v[34:35], v[178:179] op_sel_hi:[1,0]
	v_pk_mul_f32 v[24:25], v[24:25], v[178:179] op_sel_hi:[1,0]
	v_pk_mul_f32 v[26:27], v[26:27], v[178:179] op_sel_hi:[1,0]
	v_pk_mul_f32 v[28:29], v[28:29], v[176:177] op_sel_hi:[1,0]
	v_pk_mul_f32 v[30:31], v[30:31], v[176:177] op_sel_hi:[1,0]
	v_pk_mul_f32 v[20:21], v[20:21], v[176:177] op_sel_hi:[1,0]
	v_pk_mul_f32 v[22:23], v[22:23], v[176:177] op_sel_hi:[1,0]
	v_exp_f32_e32 v32, v32
	v_exp_f32_e32 v33, v33
	v_exp_f32_e32 v34, v34
	v_exp_f32_e32 v35, v35
	v_exp_f32_e32 v24, v24
	v_exp_f32_e32 v25, v25
	v_exp_f32_e32 v26, v26
	v_exp_f32_e32 v27, v27
	v_pk_add_f32 v[32:33], v[32:33], v[220:221] op_sel_hi:[1,0]
	v_pk_add_f32 v[34:35], v[34:35], v[220:221] op_sel_hi:[1,0]
	v_pk_add_f32 v[24:25], v[24:25], v[220:221] op_sel_hi:[1,0]
	v_pk_add_f32 v[26:27], v[26:27], v[220:221] op_sel_hi:[1,0]
	v_rcp_f32_e32 v32, v32
	v_rcp_f32_e32 v33, v33
	v_rcp_f32_e32 v34, v34
	v_rcp_f32_e32 v35, v35
	v_rcp_f32_e32 v24, v24
	v_rcp_f32_e32 v25, v25
	v_rcp_f32_e32 v26, v26
	v_rcp_f32_e32 v27, v27
	v_pk_mul_f32 v[32:33], v[28:29], v[32:33]
	v_pk_mul_f32 v[34:35], v[30:31], v[34:35]
	v_pk_mul_f32 v[24:25], v[20:21], v[24:25]
	v_pk_mul_f32 v[26:27], v[22:23], v[26:27]
	v_cvt_pk_bf16_f32 v32, v32, v33
	v_cvt_pk_bf16_f32 v33, v34, v35
	v_cvt_pk_bf16_f32 v34, v24, v25
	v_cvt_pk_bf16_f32 v35, v26, v27
	global_store_dwordx4 v190, v[32:35], s[28:29]
	v_mul_f32_e32 v182, 0xbfb8aa3b, v180
	v_mul_f32_e32 v180, v180, v180
	v_pk_mul_f32 v[12:13], v[16:17], v[12:13]
	v_pk_mul_f32 v[14:15], v[18:19], v[14:15]
	v_pk_mul_f32 v[4:5], v[8:9], v[4:5]
	v_pk_mul_f32 v[6:7], v[10:11], v[6:7]
	v_pk_mul_f32 v[16:17], v[16:17], v[182:183] op_sel_hi:[1,0]
	v_pk_mul_f32 v[18:19], v[18:19], v[182:183] op_sel_hi:[1,0]
	v_pk_mul_f32 v[8:9], v[8:9], v[182:183] op_sel_hi:[1,0]
	v_pk_mul_f32 v[10:11], v[10:11], v[182:183] op_sel_hi:[1,0]
	v_pk_mul_f32 v[12:13], v[12:13], v[180:181] op_sel_hi:[1,0]
	v_pk_mul_f32 v[14:15], v[14:15], v[180:181] op_sel_hi:[1,0]
	v_pk_mul_f32 v[4:5], v[4:5], v[180:181] op_sel_hi:[1,0]
	v_pk_mul_f32 v[6:7], v[6:7], v[180:181] op_sel_hi:[1,0]
	v_exp_f32_e32 v16, v16
	v_exp_f32_e32 v17, v17
	v_exp_f32_e32 v18, v18
	v_exp_f32_e32 v19, v19
	v_exp_f32_e32 v8, v8
	v_exp_f32_e32 v9, v9
	v_exp_f32_e32 v10, v10
	v_exp_f32_e32 v11, v11
	v_pk_add_f32 v[16:17], v[16:17], v[220:221] op_sel_hi:[1,0]
	v_pk_add_f32 v[18:19], v[18:19], v[220:221] op_sel_hi:[1,0]
	v_pk_add_f32 v[8:9], v[8:9], v[220:221] op_sel_hi:[1,0]
	v_pk_add_f32 v[10:11], v[10:11], v[220:221] op_sel_hi:[1,0]
	v_rcp_f32_e32 v16, v16
	v_rcp_f32_e32 v17, v17
	v_rcp_f32_e32 v18, v18
	v_rcp_f32_e32 v19, v19
	v_rcp_f32_e32 v8, v8
	v_rcp_f32_e32 v9, v9
	v_rcp_f32_e32 v10, v10
	v_rcp_f32_e32 v11, v11
	v_pk_mul_f32 v[16:17], v[12:13], v[16:17]
	v_pk_mul_f32 v[18:19], v[14:15], v[18:19]
	v_pk_mul_f32 v[8:9], v[4:5], v[8:9]
	v_pk_mul_f32 v[10:11], v[6:7], v[10:11]
	v_cvt_pk_bf16_f32 v16, v16, v17
	v_cvt_pk_bf16_f32 v17, v18, v19
	v_cvt_pk_bf16_f32 v18, v8, v9
	v_cvt_pk_bf16_f32 v19, v10, v11
	global_store_dwordx4 v191, v[16:19], s[28:29]
	s_mov_b32 s23, 0x800000
	v_readlane_b32 s60, v253, 3
	s_mov_b32 s99, 0x800000
	v_readlane_b32 s61, v253, 4
	v_readlane_b32 s62, v253, 5
	v_readlane_b32 s63, v253, 6
	s_andn2_b64 vcc, exec, s[2:3]
	s_mov_b64 s[28:29], -1
	s_cbranch_vccnz .LBB0_603
; #define PG8_BAR __builtin_amdgcn_s_barrier()
; template <class Epi, class Sched, bool ALIGN_EPI = false, bool SP2 = false>
; __device__ __forceinline__ void gemm_phase(PG8_LAS unsigned char* lds, const Gemm g, const Sched& S, const Epi& E) {
;     ...
;         if constexpr (ALIGN_EPI) { if (wr == 1) PG8_BAR; }
;     }
	s_andn2_b64 vcc, exec, s[14:15]
	s_cbranch_vccnz .LBB0_602
	s_barrier
	s_branch .LBB0_602
